# SwiGLU epilogue: store data transposed across lanes (ds_bpermute) so 4 consecutive lanes write 64 contiguous bytes
# baseline (speedup 1.0000x reference)
; __device__ __forceinline__ unsigned cvt_pk_bf16(float lo, float hi) { const f32x2 v = {lo, hi}; return __builtin_bit_cast(unsigned, __builtin_convertvector(v, bf16v2_t)); }
; __device__ __forceinline__ float silu_f(float v) { return v * __builtin_amdgcn_rcpf(1.0f + fexp(-v)); }
;     __device__ __forceinline__ void operator()(const f32x4 (&acc)[2][2][4][2], const pg8::Unit& u, int wr, int wc, int fr, int fq) const {
;         const int row0 = u.pm * 256 + wr * 64 + fr, hc0 = u.pn * 128 + wc * 32 + 8 * fq;
; #pragma unroll
;         for (int ai = 0; ai < 2; ++ai)
; #pragma unroll
;             for (int m = 0; m < 4; ++m) { u32x4 w;
; #pragma unroll
;                 for (int n = 0; n < 2; ++n) { const f32x4 a = acc[ai][0][m][n], b = acc[ai][1][m][n];
;                     w[2 * n] = cvt_pk_bf16(silu_f(a[0]) * b[0], silu_f(a[1]) * b[1]); w[2 * n + 1] = cvt_pk_bf16(silu_f(a[2]) * b[2], silu_f(a[3]) * b[3]); }
;                 const int row = row0 + ai * 128 + m * 16;
;                 *(u32x4*)(hid + ((size_t)((row >> 8) * (DFF / 64) + (hc0 >> 6)) * 2 + ((row >> 7) & 1)) * 8192 + (row & 127) * 64 + (hc0 & 63)) = w; }
.LBB0_614:
	v_mov_b32_e32 v214, 0xbfb8aa3b
	v_mov_b32_e32 v215, 0xbfb8aa3b
	v_lshrrev_b32_e32 v236, 2, v193
	v_and_b32_e32 v237, 3, v193
	v_lshlrev_b32_e32 v237, 4, v237
	v_or_b32_e32 v242, v237, v236
	v_lshlrev_b32_e32 v242, 2, v242
	v_and_b32_e32 v244, -16, v140
	v_or_b32_e32 v244, v244, v236
	v_and_b32_e32 v246, 0xffffffcf, v138
	v_or_b32_e32 v246, v246, v237
	v_mov_b32_e32 v247, v1
	v_pk_mul_f32 v[206:207], v[126:127], v[214:215] op_sel_hi:[1,0]
	v_pk_mul_f32 v[208:209], v[128:129], v[214:215] op_sel_hi:[1,0]
	v_pk_mul_f32 v[210:211], v[118:119], v[214:215] op_sel_hi:[1,0]
	v_pk_mul_f32 v[212:213], v[120:121], v[214:215] op_sel_hi:[1,0]
	v_exp_f32_e32 v206, v206
	v_exp_f32_e32 v207, v207
	v_exp_f32_e32 v208, v208
	v_exp_f32_e32 v209, v209
	v_exp_f32_e32 v210, v210
	v_exp_f32_e32 v211, v211
	v_exp_f32_e32 v212, v212
	v_exp_f32_e32 v213, v213
	v_pk_add_f32 v[206:207], v[206:207], 1.0 op_sel_hi:[1,0]
	v_pk_add_f32 v[208:209], v[208:209], 1.0 op_sel_hi:[1,0]
	v_pk_add_f32 v[210:211], v[210:211], 1.0 op_sel_hi:[1,0]
	v_pk_add_f32 v[212:213], v[212:213], 1.0 op_sel_hi:[1,0]
	v_rcp_f32_e32 v206, v206
	v_rcp_f32_e32 v207, v207
	v_rcp_f32_e32 v208, v208
	v_rcp_f32_e32 v209, v209
	v_rcp_f32_e32 v210, v210
	v_rcp_f32_e32 v211, v211
	v_rcp_f32_e32 v212, v212
	v_rcp_f32_e32 v213, v213
	v_pk_mul_f32 v[206:207], v[126:127], v[206:207]
	v_pk_mul_f32 v[208:209], v[128:129], v[208:209]
	v_pk_mul_f32 v[210:211], v[118:119], v[210:211]
	v_pk_mul_f32 v[212:213], v[120:121], v[212:213]
	v_pk_mul_f32 v[206:207], v[206:207], v[122:123]
	v_pk_mul_f32 v[208:209], v[208:209], v[124:125]
	v_pk_mul_f32 v[210:211], v[210:211], v[114:115]
	v_pk_mul_f32 v[212:213], v[212:213], v[116:117]
	v_cvt_pk_bf16_f32 v122, v206, v207
	v_cvt_pk_bf16_f32 v123, v208, v209
	v_cvt_pk_bf16_f32 v124, v210, v211
	v_cvt_pk_bf16_f32 v125, v212, v213
	ds_bpermute_b32 v216, v242, v122
	ds_bpermute_b32 v217, v242, v123
	ds_bpermute_b32 v218, v242, v124
	ds_bpermute_b32 v219, v242, v125
	v_pk_mul_f32 v[206:207], v[110:111], v[214:215] op_sel_hi:[1,0]
	v_pk_mul_f32 v[208:209], v[112:113], v[214:215] op_sel_hi:[1,0]
	v_pk_mul_f32 v[210:211], v[102:103], v[214:215] op_sel_hi:[1,0]
	v_pk_mul_f32 v[212:213], v[104:105], v[214:215] op_sel_hi:[1,0]
	v_exp_f32_e32 v206, v206
	v_exp_f32_e32 v207, v207
	v_exp_f32_e32 v208, v208
	v_exp_f32_e32 v209, v209
	v_exp_f32_e32 v210, v210
	v_exp_f32_e32 v211, v211
	v_exp_f32_e32 v212, v212
	v_exp_f32_e32 v213, v213
	v_pk_add_f32 v[206:207], v[206:207], 1.0 op_sel_hi:[1,0]
	v_pk_add_f32 v[208:209], v[208:209], 1.0 op_sel_hi:[1,0]
	v_pk_add_f32 v[210:211], v[210:211], 1.0 op_sel_hi:[1,0]
	v_pk_add_f32 v[212:213], v[212:213], 1.0 op_sel_hi:[1,0]
	v_rcp_f32_e32 v206, v206
	v_rcp_f32_e32 v207, v207
	v_rcp_f32_e32 v208, v208
	v_rcp_f32_e32 v209, v209
	v_rcp_f32_e32 v210, v210
	v_rcp_f32_e32 v211, v211
	v_rcp_f32_e32 v212, v212
	v_rcp_f32_e32 v213, v213
	v_pk_mul_f32 v[206:207], v[110:111], v[206:207]
	v_pk_mul_f32 v[208:209], v[112:113], v[208:209]
	v_pk_mul_f32 v[210:211], v[102:103], v[210:211]
	v_pk_mul_f32 v[212:213], v[104:105], v[212:213]
	v_pk_mul_f32 v[206:207], v[206:207], v[106:107]
	v_pk_mul_f32 v[208:209], v[208:209], v[108:109]
	v_pk_mul_f32 v[210:211], v[210:211], v[98:99]
	v_pk_mul_f32 v[212:213], v[212:213], v[100:101]
	v_cvt_pk_bf16_f32 v106, v206, v207
	v_cvt_pk_bf16_f32 v107, v208, v209
	v_cvt_pk_bf16_f32 v108, v210, v211
	v_cvt_pk_bf16_f32 v109, v212, v213
	ds_bpermute_b32 v220, v242, v106
	ds_bpermute_b32 v221, v242, v107
	ds_bpermute_b32 v222, v242, v108
	ds_bpermute_b32 v223, v242, v109
	s_waitcnt lgkmcnt(4)
	s_lshl_b32 s13, s18, 8
	s_add_i32 s13, s13, s38
	s_lshl_b32 s11, s19, 7
	s_or_b32 s11, s11, s39
	s_ashr_i32 s18, s13, 8
	s_ashr_i32 s11, s11, 6
	s_mul_i32 s18, s18, 44
	s_add_i32 s18, s18, s11
	s_ashr_i32 s19, s18, 31
	s_lshl_b64 s[18:19], s[18:19], 15
	v_readlane_b32 s20, v249, 53
	v_readlane_b32 s21, v249, 54
	s_add_u32 s18, s20, s18
	v_or_b32_e32 v143, s13, v244
	s_addc_u32 s19, s21, s19
	s_lshl_b32 s13, s13, 7
	s_and_b32 s13, s13, 0x4000
	s_add_u32 s18, s18, s13
	s_addc_u32 s19, s19, 0
	v_mov_b32_e32 v139, v1
	v_lshlrev_b32_e32 v0, 7, v143
	v_and_b32_e32 v0, 0x2780, v0
	s_andn2_b64 vcc, exec, s[0:1]
	v_lshl_add_u64 v[114:115], s[18:19], 0, v[0:1]
	v_lshl_add_u64 v[114:115], v[114:115], 0, v[246:247]
	global_store_dwordx4 v[114:115], v[216:219], off
	v_pk_mul_f32 v[206:207], v[94:95], v[214:215] op_sel_hi:[1,0]
	v_pk_mul_f32 v[208:209], v[96:97], v[214:215] op_sel_hi:[1,0]
	v_pk_mul_f32 v[210:211], v[86:87], v[214:215] op_sel_hi:[1,0]
	v_pk_mul_f32 v[212:213], v[88:89], v[214:215] op_sel_hi:[1,0]
	v_exp_f32_e32 v206, v206
	v_exp_f32_e32 v207, v207
	v_exp_f32_e32 v208, v208
	v_exp_f32_e32 v209, v209
	v_exp_f32_e32 v210, v210
	v_exp_f32_e32 v211, v211
	v_exp_f32_e32 v212, v212
	v_exp_f32_e32 v213, v213
	v_pk_add_f32 v[206:207], v[206:207], 1.0 op_sel_hi:[1,0]
	v_pk_add_f32 v[208:209], v[208:209], 1.0 op_sel_hi:[1,0]
	v_pk_add_f32 v[210:211], v[210:211], 1.0 op_sel_hi:[1,0]
	v_pk_add_f32 v[212:213], v[212:213], 1.0 op_sel_hi:[1,0]
	v_rcp_f32_e32 v206, v206
	v_rcp_f32_e32 v207, v207
	v_rcp_f32_e32 v208, v208
	v_rcp_f32_e32 v209, v209
	v_rcp_f32_e32 v210, v210
	v_rcp_f32_e32 v211, v211
	v_rcp_f32_e32 v212, v212
	v_rcp_f32_e32 v213, v213
	v_pk_mul_f32 v[206:207], v[94:95], v[206:207]
	v_pk_mul_f32 v[208:209], v[96:97], v[208:209]
	v_pk_mul_f32 v[210:211], v[86:87], v[210:211]
	v_pk_mul_f32 v[212:213], v[88:89], v[212:213]
	v_pk_mul_f32 v[206:207], v[206:207], v[90:91]
	v_pk_mul_f32 v[208:209], v[208:209], v[92:93]
	v_pk_mul_f32 v[210:211], v[210:211], v[82:83]
	v_pk_mul_f32 v[212:213], v[212:213], v[84:85]
	v_cvt_pk_bf16_f32 v90, v206, v207
	v_cvt_pk_bf16_f32 v91, v208, v209
	v_cvt_pk_bf16_f32 v92, v210, v211
	v_cvt_pk_bf16_f32 v93, v212, v213
	ds_bpermute_b32 v216, v242, v90
	ds_bpermute_b32 v217, v242, v91
	ds_bpermute_b32 v218, v242, v92
	ds_bpermute_b32 v219, v242, v93
	s_waitcnt lgkmcnt(4)
; __device__ __forceinline__ unsigned cvt_pk_bf16(float lo, float hi) { const f32x2 v = {lo, hi}; return __builtin_bit_cast(unsigned, __builtin_convertvector(v, bf16v2_t)); }
; __device__ __forceinline__ float silu_f(float v) { return v * __builtin_amdgcn_rcpf(1.0f + fexp(-v)); }
;     __device__ __forceinline__ void operator()(const f32x4 (&acc)[2][2][4][2], const pg8::Unit& u, int wr, int wc, int fr, int fq) const {
;         const int row0 = u.pm * 256 + wr * 64 + fr, hc0 = u.pn * 128 + wc * 32 + 8 * fq;
; #pragma unroll
;         for (int ai = 0; ai < 2; ++ai)
; #pragma unroll
;             for (int m = 0; m < 4; ++m) { u32x4 w;
; #pragma unroll
;                 for (int n = 0; n < 2; ++n) { const f32x4 a = acc[ai][0][m][n], b = acc[ai][1][m][n];
;                     w[2 * n] = cvt_pk_bf16(silu_f(a[0]) * b[0], silu_f(a[1]) * b[1]); w[2 * n + 1] = cvt_pk_bf16(silu_f(a[2]) * b[2], silu_f(a[3]) * b[3]); }
;                 const int row = row0 + ai * 128 + m * 16;
;                 *(u32x4*)(hid + ((size_t)((row >> 8) * (DFF / 64) + (hc0 >> 6)) * 2 + ((row >> 7) & 1)) * 8192 + (row & 127) * 64 + (hc0 & 63)) = w; }
	global_store_dwordx4 v[114:115], v[220:223], off offset:2048
	v_pk_mul_f32 v[206:207], v[78:79], v[214:215] op_sel_hi:[1,0]
	v_pk_mul_f32 v[208:209], v[80:81], v[214:215] op_sel_hi:[1,0]
	v_pk_mul_f32 v[210:211], v[70:71], v[214:215] op_sel_hi:[1,0]
	v_pk_mul_f32 v[212:213], v[72:73], v[214:215] op_sel_hi:[1,0]
	v_exp_f32_e32 v206, v206
	v_exp_f32_e32 v207, v207
	v_exp_f32_e32 v208, v208
	v_exp_f32_e32 v209, v209
	v_exp_f32_e32 v210, v210
	v_exp_f32_e32 v211, v211
	v_exp_f32_e32 v212, v212
	v_exp_f32_e32 v213, v213
	v_pk_add_f32 v[206:207], v[206:207], 1.0 op_sel_hi:[1,0]
	v_pk_add_f32 v[208:209], v[208:209], 1.0 op_sel_hi:[1,0]
	v_pk_add_f32 v[210:211], v[210:211], 1.0 op_sel_hi:[1,0]
	v_pk_add_f32 v[212:213], v[212:213], 1.0 op_sel_hi:[1,0]
	v_rcp_f32_e32 v206, v206
	v_rcp_f32_e32 v207, v207
	v_rcp_f32_e32 v208, v208
	v_rcp_f32_e32 v209, v209
	v_rcp_f32_e32 v210, v210
	v_rcp_f32_e32 v211, v211
	v_rcp_f32_e32 v212, v212
	v_rcp_f32_e32 v213, v213
	v_pk_mul_f32 v[206:207], v[78:79], v[206:207]
	v_pk_mul_f32 v[208:209], v[80:81], v[208:209]
	v_pk_mul_f32 v[210:211], v[70:71], v[210:211]
	v_pk_mul_f32 v[212:213], v[72:73], v[212:213]
	v_pk_mul_f32 v[206:207], v[206:207], v[74:75]
	v_pk_mul_f32 v[208:209], v[208:209], v[76:77]
	v_pk_mul_f32 v[210:211], v[210:211], v[66:67]
	v_pk_mul_f32 v[212:213], v[212:213], v[68:69]
	v_cvt_pk_bf16_f32 v74, v206, v207
	v_cvt_pk_bf16_f32 v75, v208, v209
	v_cvt_pk_bf16_f32 v76, v210, v211
	v_cvt_pk_bf16_f32 v77, v212, v213
	ds_bpermute_b32 v220, v242, v74
	ds_bpermute_b32 v221, v242, v75
	ds_bpermute_b32 v222, v242, v76
	ds_bpermute_b32 v223, v242, v77
	s_waitcnt lgkmcnt(4)
	v_or_b32_e32 v82, 0x1000, v0
	v_mov_b32_e32 v83, v1
	v_lshl_add_u64 v[84:85], s[18:19], 0, v[82:83]
	v_lshl_add_u64 v[84:85], v[84:85], 0, v[246:247]
	global_store_dwordx4 v[84:85], v[216:219], off
	v_pk_mul_f32 v[206:207], v[62:63], v[214:215] op_sel_hi:[1,0]
	v_pk_mul_f32 v[208:209], v[64:65], v[214:215] op_sel_hi:[1,0]
	v_pk_mul_f32 v[210:211], v[54:55], v[214:215] op_sel_hi:[1,0]
	v_pk_mul_f32 v[212:213], v[56:57], v[214:215] op_sel_hi:[1,0]
	v_exp_f32_e32 v206, v206
	v_exp_f32_e32 v207, v207
	v_exp_f32_e32 v208, v208
	v_exp_f32_e32 v209, v209
	v_exp_f32_e32 v210, v210
	v_exp_f32_e32 v211, v211
	v_exp_f32_e32 v212, v212
	v_exp_f32_e32 v213, v213
	v_pk_add_f32 v[206:207], v[206:207], 1.0 op_sel_hi:[1,0]
	v_pk_add_f32 v[208:209], v[208:209], 1.0 op_sel_hi:[1,0]
	v_pk_add_f32 v[210:211], v[210:211], 1.0 op_sel_hi:[1,0]
	v_pk_add_f32 v[212:213], v[212:213], 1.0 op_sel_hi:[1,0]
	v_rcp_f32_e32 v206, v206
	v_rcp_f32_e32 v207, v207
	v_rcp_f32_e32 v208, v208
	v_rcp_f32_e32 v209, v209
	v_rcp_f32_e32 v210, v210
	v_rcp_f32_e32 v211, v211
	v_rcp_f32_e32 v212, v212
	v_rcp_f32_e32 v213, v213
	v_pk_mul_f32 v[206:207], v[62:63], v[206:207]
	v_pk_mul_f32 v[208:209], v[64:65], v[208:209]
	v_pk_mul_f32 v[210:211], v[54:55], v[210:211]
	v_pk_mul_f32 v[212:213], v[56:57], v[212:213]
	v_pk_mul_f32 v[206:207], v[206:207], v[58:59]
	v_pk_mul_f32 v[208:209], v[208:209], v[60:61]
	v_pk_mul_f32 v[210:211], v[210:211], v[50:51]
	v_pk_mul_f32 v[212:213], v[212:213], v[52:53]
	v_cvt_pk_bf16_f32 v58, v206, v207
	v_cvt_pk_bf16_f32 v59, v208, v209
	v_cvt_pk_bf16_f32 v60, v210, v211
	v_cvt_pk_bf16_f32 v61, v212, v213
	ds_bpermute_b32 v216, v242, v58
	ds_bpermute_b32 v217, v242, v59
	ds_bpermute_b32 v218, v242, v60
	ds_bpermute_b32 v219, v242, v61
	s_waitcnt lgkmcnt(4)
	v_add_u32_e32 v72, 0x80, v143
	v_or_b32_e32 v66, 0x1800, v0
	v_mov_b32_e32 v67, v1
	v_lshl_add_u64 v[68:69], s[18:19], 0, v[66:67]
	v_lshl_add_u64 v[68:69], v[68:69], 0, v[246:247]
	global_store_dwordx4 v[68:69], v[220:223], off
	v_pk_mul_f32 v[206:207], v[46:47], v[214:215] op_sel_hi:[1,0]
	v_pk_mul_f32 v[208:209], v[48:49], v[214:215] op_sel_hi:[1,0]
	v_pk_mul_f32 v[210:211], v[38:39], v[214:215] op_sel_hi:[1,0]
	v_pk_mul_f32 v[212:213], v[40:41], v[214:215] op_sel_hi:[1,0]
	v_exp_f32_e32 v206, v206
	v_exp_f32_e32 v207, v207
	v_exp_f32_e32 v208, v208
	v_exp_f32_e32 v209, v209
	v_exp_f32_e32 v210, v210
	v_exp_f32_e32 v211, v211
	v_exp_f32_e32 v212, v212
	v_exp_f32_e32 v213, v213
	v_pk_add_f32 v[206:207], v[206:207], 1.0 op_sel_hi:[1,0]
	v_pk_add_f32 v[208:209], v[208:209], 1.0 op_sel_hi:[1,0]
	v_pk_add_f32 v[210:211], v[210:211], 1.0 op_sel_hi:[1,0]
	v_pk_add_f32 v[212:213], v[212:213], 1.0 op_sel_hi:[1,0]
	v_rcp_f32_e32 v206, v206
	v_rcp_f32_e32 v207, v207
	v_rcp_f32_e32 v208, v208
	v_rcp_f32_e32 v209, v209
	v_rcp_f32_e32 v210, v210
	v_rcp_f32_e32 v211, v211
	v_rcp_f32_e32 v212, v212
	v_rcp_f32_e32 v213, v213
	v_pk_mul_f32 v[206:207], v[46:47], v[206:207]
	v_pk_mul_f32 v[208:209], v[48:49], v[208:209]
	v_pk_mul_f32 v[210:211], v[38:39], v[210:211]
	v_pk_mul_f32 v[212:213], v[40:41], v[212:213]
	v_pk_mul_f32 v[206:207], v[206:207], v[42:43]
	v_pk_mul_f32 v[208:209], v[208:209], v[44:45]
	v_pk_mul_f32 v[210:211], v[210:211], v[34:35]
	v_pk_mul_f32 v[212:213], v[212:213], v[36:37]
	v_cvt_pk_bf16_f32 v42, v206, v207
	v_cvt_pk_bf16_f32 v43, v208, v209
	v_cvt_pk_bf16_f32 v44, v210, v211
	v_cvt_pk_bf16_f32 v45, v212, v213
	ds_bpermute_b32 v220, v242, v42
	ds_bpermute_b32 v221, v242, v43
	ds_bpermute_b32 v222, v242, v44
	ds_bpermute_b32 v223, v242, v45
	s_waitcnt lgkmcnt(4)
; __device__ __forceinline__ unsigned cvt_pk_bf16(float lo, float hi) { const f32x2 v = {lo, hi}; return __builtin_bit_cast(unsigned, __builtin_convertvector(v, bf16v2_t)); }
; __device__ __forceinline__ float silu_f(float v) { return v * __builtin_amdgcn_rcpf(1.0f + fexp(-v)); }
;     __device__ __forceinline__ void operator()(const f32x4 (&acc)[2][2][4][2], const pg8::Unit& u, int wr, int wc, int fr, int fq) const {
;         const int row0 = u.pm * 256 + wr * 64 + fr, hc0 = u.pn * 128 + wc * 32 + 8 * fq;
; #pragma unroll
;         for (int ai = 0; ai < 2; ++ai)
; #pragma unroll
;             for (int m = 0; m < 4; ++m) { u32x4 w;
; #pragma unroll
;                 for (int n = 0; n < 2; ++n) { const f32x4 a = acc[ai][0][m][n], b = acc[ai][1][m][n];
;                     w[2 * n] = cvt_pk_bf16(silu_f(a[0]) * b[0], silu_f(a[1]) * b[1]); w[2 * n + 1] = cvt_pk_bf16(silu_f(a[2]) * b[2], silu_f(a[3]) * b[3]); }
;                 const int row = row0 + ai * 128 + m * 16;
;                 *(u32x4*)(hid + ((size_t)((row >> 8) * (DFF / 64) + (hc0 >> 6)) * 2 + ((row >> 7) & 1)) * 8192 + (row & 127) * 64 + (hc0 & 63)) = w; }
	v_lshrrev_b32_e32 v68, 8, v72
	v_mad_i32_i24 v68, v68, 44, s11
	v_ashrrev_i32_e32 v69, 31, v68
	v_lshlrev_b64 v[68:69], 15, v[68:69]
	s_mov_b64 s[18:19], -1
	v_lshlrev_b32_e32 v52, 7, v72
	v_lshl_add_u64 v[50:51], s[20:21], 0, v[68:69]
	v_and_b32_e32 v52, 0x4000, v52
	v_mov_b32_e32 v53, v1
	v_lshl_add_u64 v[50:51], v[50:51], 0, v[52:53]
	v_lshl_add_u64 v[52:53], v[50:51], 0, v[0:1]
	v_lshl_add_u64 v[52:53], v[52:53], 0, v[246:247]
	global_store_dwordx4 v[52:53], v[216:219], off
	v_pk_mul_f32 v[206:207], v[30:31], v[214:215] op_sel_hi:[1,0]
	v_pk_mul_f32 v[208:209], v[32:33], v[214:215] op_sel_hi:[1,0]
	v_pk_mul_f32 v[210:211], v[22:23], v[214:215] op_sel_hi:[1,0]
	v_pk_mul_f32 v[212:213], v[24:25], v[214:215] op_sel_hi:[1,0]
	v_exp_f32_e32 v206, v206
	v_exp_f32_e32 v207, v207
	v_exp_f32_e32 v208, v208
	v_exp_f32_e32 v209, v209
	v_exp_f32_e32 v210, v210
	v_exp_f32_e32 v211, v211
	v_exp_f32_e32 v212, v212
	v_exp_f32_e32 v213, v213
	v_pk_add_f32 v[206:207], v[206:207], 1.0 op_sel_hi:[1,0]
	v_pk_add_f32 v[208:209], v[208:209], 1.0 op_sel_hi:[1,0]
	v_pk_add_f32 v[210:211], v[210:211], 1.0 op_sel_hi:[1,0]
	v_pk_add_f32 v[212:213], v[212:213], 1.0 op_sel_hi:[1,0]
	v_rcp_f32_e32 v206, v206
	v_rcp_f32_e32 v207, v207
	v_rcp_f32_e32 v208, v208
	v_rcp_f32_e32 v209, v209
	v_rcp_f32_e32 v210, v210
	v_rcp_f32_e32 v211, v211
	v_rcp_f32_e32 v212, v212
	v_rcp_f32_e32 v213, v213
	v_pk_mul_f32 v[206:207], v[30:31], v[206:207]
	v_pk_mul_f32 v[208:209], v[32:33], v[208:209]
	v_pk_mul_f32 v[210:211], v[22:23], v[210:211]
	v_pk_mul_f32 v[212:213], v[24:25], v[212:213]
	v_pk_mul_f32 v[206:207], v[206:207], v[26:27]
	v_pk_mul_f32 v[208:209], v[208:209], v[28:29]
	v_pk_mul_f32 v[210:211], v[210:211], v[18:19]
	v_pk_mul_f32 v[212:213], v[212:213], v[20:21]
	v_cvt_pk_bf16_f32 v26, v206, v207
	v_cvt_pk_bf16_f32 v27, v208, v209
	v_cvt_pk_bf16_f32 v28, v210, v211
	v_cvt_pk_bf16_f32 v29, v212, v213
	ds_bpermute_b32 v216, v242, v26
	ds_bpermute_b32 v217, v242, v27
	ds_bpermute_b32 v218, v242, v28
	ds_bpermute_b32 v219, v242, v29
	s_waitcnt lgkmcnt(4)
	global_store_dwordx4 v[52:53], v[220:223], off offset:2048
	v_pk_mul_f32 v[206:207], v[14:15], v[214:215] op_sel_hi:[1,0]
	v_pk_mul_f32 v[208:209], v[16:17], v[214:215] op_sel_hi:[1,0]
	v_pk_mul_f32 v[210:211], v[6:7], v[214:215] op_sel_hi:[1,0]
	v_pk_mul_f32 v[212:213], v[8:9], v[214:215] op_sel_hi:[1,0]
	v_exp_f32_e32 v206, v206
	v_exp_f32_e32 v207, v207
	v_exp_f32_e32 v208, v208
	v_exp_f32_e32 v209, v209
	v_exp_f32_e32 v210, v210
	v_exp_f32_e32 v211, v211
	v_exp_f32_e32 v212, v212
	v_exp_f32_e32 v213, v213
	v_pk_add_f32 v[206:207], v[206:207], 1.0 op_sel_hi:[1,0]
	v_pk_add_f32 v[208:209], v[208:209], 1.0 op_sel_hi:[1,0]
	v_pk_add_f32 v[210:211], v[210:211], 1.0 op_sel_hi:[1,0]
	v_pk_add_f32 v[212:213], v[212:213], 1.0 op_sel_hi:[1,0]
	v_rcp_f32_e32 v206, v206
	v_rcp_f32_e32 v207, v207
	v_rcp_f32_e32 v208, v208
	v_rcp_f32_e32 v209, v209
	v_rcp_f32_e32 v210, v210
	v_rcp_f32_e32 v211, v211
	v_rcp_f32_e32 v212, v212
	v_rcp_f32_e32 v213, v213
	v_pk_mul_f32 v[206:207], v[14:15], v[206:207]
	v_pk_mul_f32 v[208:209], v[16:17], v[208:209]
	v_pk_mul_f32 v[210:211], v[6:7], v[210:211]
	v_pk_mul_f32 v[212:213], v[8:9], v[212:213]
	v_pk_mul_f32 v[206:207], v[206:207], v[10:11]
	v_pk_mul_f32 v[208:209], v[208:209], v[12:13]
	v_pk_mul_f32 v[210:211], v[210:211], v[2:3]
	v_pk_mul_f32 v[212:213], v[212:213], v[4:5]
	v_cvt_pk_bf16_f32 v10, v206, v207
	v_cvt_pk_bf16_f32 v11, v208, v209
	v_cvt_pk_bf16_f32 v12, v210, v211
	v_cvt_pk_bf16_f32 v13, v212, v213
	ds_bpermute_b32 v220, v242, v10
	ds_bpermute_b32 v221, v242, v11
	ds_bpermute_b32 v222, v242, v12
	ds_bpermute_b32 v223, v242, v13
	s_waitcnt lgkmcnt(4)
	v_lshl_add_u64 v[18:19], v[50:51], 0, v[82:83]
	v_lshl_add_u64 v[18:19], v[18:19], 0, v[246:247]
	global_store_dwordx4 v[18:19], v[216:219], off
	s_waitcnt lgkmcnt(0)
	v_lshl_add_u64 v[2:3], v[50:51], 0, v[66:67]
	v_lshl_add_u64 v[2:3], v[2:3], 0, v[246:247]
	global_store_dwordx4 v[2:3], v[220:223], off
	s_cbranch_vccnz .LBB0_603
	s_andn2_b64 vcc, exec, s[6:7]
	s_cbranch_vccnz .LBB0_602
	s_barrier
	s_branch .LBB0_602
